# FFN-down half-tile round: the LDS-DMA loads of the unused activation row half (phases 1 and 5) are skipped
# speedup vs baseline: 1.0045x; 1.0045x over previous
.LBB0_1247:
	s_add_u32 s16, s14, 0x100
	s_addc_u32 s17, s15, 0
	s_add_i32 s44, 0, 0x10000
	v_add_u32_e32 v110, s44, v160
	ds_read_b128 v[98:101], v110
	ds_read_b128 v[102:105], v110 offset:1024
	ds_read_b128 v[106:109], v110 offset:2048
	ds_read_b128 v[110:113], v110 offset:3072
	s_cmp_eq_u32 s43, 40
	s_cselect_b32 s21, s7, s17
	s_cselect_b32 s20, s6, s16
	s_cselect_b32 s19, s9, s42
	s_cselect_b32 s18, s8, s41
	v_lshl_add_u64 v[172:173], s[14:15], 0, v[150:151]
	s_add_i32 m0, s25, 0xc000
	ds_read_b128 v[152:155], v161
	ds_read_b128 v[156:159], v161 offset:1024
	ds_read_b128 v[176:179], v161 offset:2048
	ds_read_b128 v[180:183], v161 offset:3072
	ds_read_b128 v[184:187], v161 offset:4096
	ds_read_b128 v[188:191], v161 offset:5120
	ds_read_b128 v[192:195], v161 offset:6144
	ds_read_b128 v[196:199], v161 offset:7168
	s_cmp_lg_u32 s99, 0
	s_cbranch_scc1 .Lhsd0_0
	global_load_lds_dwordx4 v[172:173], off
.Lhsd0_0:
	v_lshl_add_u64 v[172:173], s[14:15], 0, v[148:149]
	s_add_i32 m0, s25, 0xe000
	s_nop 0
	s_cmp_lg_u32 s99, 0
	s_cbranch_scc1 .Lhsd0_1
	global_load_lds_dwordx4 v[172:173], off
.Lhsd0_1:
	s_waitcnt lgkmcnt(8)
	s_barrier
	s_waitcnt lgkmcnt(0)
	s_setprio 1
	s_waitcnt lgkmcnt(0)
	v_mfma_f32_16x16x32_bf16 v[142:145], v[98:101], v[152:155], v[142:145]
	v_mfma_f32_16x16x32_bf16 v[138:141], v[106:109], v[152:155], v[138:141]
	v_mfma_f32_16x16x32_bf16 v[134:137], v[98:101], v[176:179], v[134:137]
	v_mfma_f32_16x16x32_bf16 v[122:125], v[106:109], v[176:179], v[122:125]
	v_mfma_f32_16x16x32_bf16 v[94:97], v[98:101], v[184:187], v[94:97]
	v_mfma_f32_16x16x32_bf16 v[90:93], v[106:109], v[184:187], v[90:93]
	v_mfma_f32_16x16x32_bf16 v[86:89], v[98:101], v[192:195], v[86:89]
	v_mfma_f32_16x16x32_bf16 v[74:77], v[106:109], v[192:195], v[74:77]
	v_mfma_f32_16x16x32_bf16 v[142:145], v[102:105], v[156:159], v[142:145]
	v_mfma_f32_16x16x32_bf16 v[138:141], v[110:113], v[156:159], v[138:141]
	v_mfma_f32_16x16x32_bf16 v[134:137], v[102:105], v[180:183], v[134:137]
	v_mfma_f32_16x16x32_bf16 v[122:125], v[110:113], v[180:183], v[122:125]
	v_mfma_f32_16x16x32_bf16 v[94:97], v[102:105], v[188:191], v[94:97]
	v_mfma_f32_16x16x32_bf16 v[90:93], v[110:113], v[188:191], v[90:93]
	v_mfma_f32_16x16x32_bf16 v[86:89], v[102:105], v[196:199], v[86:89]
	v_mfma_f32_16x16x32_bf16 v[74:77], v[110:113], v[196:199], v[74:77]
	s_setprio 0
	s_barrier
	s_add_i32 s45, 0, 0x14000
	s_add_i32 s14, s44, s23
	v_add_u32_e32 v169, s45, v160
	v_lshl_add_u64 v[172:173], s[18:19], 0, v[0:1]
	s_mov_b32 m0, s14
	ds_read_b128 v[230:233], v169
	ds_read_b128 v[234:237], v169 offset:1024
	ds_read_b128 v[238:241], v169 offset:2048
	ds_read_b128 v[242:245], v169 offset:3072
	global_load_lds_dwordx4 v[172:173], off
	v_lshl_add_u64 v[174:175], s[18:19], 0, v[146:147]
	s_add_i32 m0, s14, 0x2000
	s_nop 0
	global_load_lds_dwordx4 v[174:175], off
	s_barrier
	s_waitcnt lgkmcnt(0)
	s_setprio 1
	s_waitcnt lgkmcnt(0)
	v_mfma_f32_16x16x32_bf16 v[130:133], v[230:233], v[152:155], v[130:133]
	v_mfma_f32_16x16x32_bf16 v[126:129], v[238:241], v[152:155], v[126:129]
	v_mfma_f32_16x16x32_bf16 v[118:121], v[230:233], v[176:179], v[118:121]
	v_mfma_f32_16x16x32_bf16 v[114:117], v[238:241], v[176:179], v[114:117]
	v_mfma_f32_16x16x32_bf16 v[82:85], v[230:233], v[184:187], v[82:85]
	v_mfma_f32_16x16x32_bf16 v[78:81], v[238:241], v[184:187], v[78:81]
	v_mfma_f32_16x16x32_bf16 v[70:73], v[230:233], v[192:195], v[70:73]
	v_mfma_f32_16x16x32_bf16 v[66:69], v[238:241], v[192:195], v[66:69]
	v_mfma_f32_16x16x32_bf16 v[130:133], v[234:237], v[156:159], v[130:133]
	v_mfma_f32_16x16x32_bf16 v[126:129], v[242:245], v[156:159], v[126:129]
	v_mfma_f32_16x16x32_bf16 v[118:121], v[234:237], v[180:183], v[118:121]
	v_mfma_f32_16x16x32_bf16 v[114:117], v[242:245], v[180:183], v[114:117]
	v_mfma_f32_16x16x32_bf16 v[82:85], v[234:237], v[188:191], v[82:85]
	v_mfma_f32_16x16x32_bf16 v[78:81], v[242:245], v[188:191], v[78:81]
	v_mfma_f32_16x16x32_bf16 v[70:73], v[234:237], v[196:199], v[70:73]
	v_mfma_f32_16x16x32_bf16 v[66:69], v[242:245], v[196:199], v[66:69]
	s_setprio 0
	s_mov_b32 m0, s25
	v_lshl_add_u64 v[200:201], s[20:21], 0, v[0:1]
	s_barrier
	ds_read_b128 v[152:155], v161 offset:16384
	ds_read_b128 v[156:159], v161 offset:17408
	ds_read_b128 v[176:179], v161 offset:18432
	ds_read_b128 v[180:183], v161 offset:19456
	ds_read_b128 v[184:187], v161 offset:20480
	ds_read_b128 v[188:191], v161 offset:21504
	ds_read_b128 v[192:195], v161 offset:22528
	ds_read_b128 v[196:199], v161 offset:23552
	global_load_lds_dwordx4 v[200:201], off
	v_lshl_add_u64 v[210:211], s[20:21], 0, v[146:147]
	s_mov_b32 m0, s26
	s_nop 0
	global_load_lds_dwordx4 v[210:211], off
	s_barrier
	s_waitcnt lgkmcnt(0)
	s_setprio 1
	s_waitcnt lgkmcnt(0)
	s_cmp_lg_u32 s99, 0
	s_cbranch_scc1 .Lfd_skip3
	v_mfma_f32_16x16x32_bf16 v[62:65], v[98:101], v[152:155], v[62:65]
	v_mfma_f32_16x16x32_bf16 v[58:61], v[106:109], v[152:155], v[58:61]
	v_mfma_f32_16x16x32_bf16 v[54:57], v[98:101], v[176:179], v[54:57]
	v_mfma_f32_16x16x32_bf16 v[42:45], v[106:109], v[176:179], v[42:45]
	v_mfma_f32_16x16x32_bf16 v[30:33], v[98:101], v[184:187], v[30:33]
	v_mfma_f32_16x16x32_bf16 v[26:29], v[106:109], v[184:187], v[26:29]
	v_mfma_f32_16x16x32_bf16 v[22:25], v[98:101], v[192:195], v[22:25]
	v_mfma_f32_16x16x32_bf16 v[18:21], v[106:109], v[192:195], v[18:21]
	v_mfma_f32_16x16x32_bf16 v[62:65], v[102:105], v[156:159], v[62:65]
	v_mfma_f32_16x16x32_bf16 v[58:61], v[110:113], v[156:159], v[58:61]
	v_mfma_f32_16x16x32_bf16 v[54:57], v[102:105], v[180:183], v[54:57]
	v_mfma_f32_16x16x32_bf16 v[42:45], v[110:113], v[180:183], v[42:45]
	v_mfma_f32_16x16x32_bf16 v[30:33], v[102:105], v[188:191], v[30:33]
	v_mfma_f32_16x16x32_bf16 v[26:29], v[110:113], v[188:191], v[26:29]
	v_mfma_f32_16x16x32_bf16 v[22:25], v[102:105], v[196:199], v[22:25]
	v_mfma_f32_16x16x32_bf16 v[18:21], v[110:113], v[196:199], v[18:21]

.Lfd_skip4:
	s_setprio 0
	s_add_i32 s44, 0, 0x18000
	v_add_u32_e32 v110, s44, v160
	s_barrier
	ds_read_b128 v[98:101], v110
	ds_read_b128 v[102:105], v110 offset:1024
	ds_read_b128 v[106:109], v110 offset:2048
	ds_read_b128 v[110:113], v110 offset:3072
	s_add_u32 s14, s20, 0xb0000
	s_addc_u32 s15, s21, 0
	s_mov_b32 m0, s27
	v_lshl_add_u64 v[230:231], s[14:15], 0, v[0:1]
	ds_read_b128 v[152:155], v161 offset:32768
	ds_read_b128 v[156:159], v161 offset:33792
	ds_read_b128 v[176:179], v161 offset:34816
	ds_read_b128 v[180:183], v161 offset:35840
	ds_read_b128 v[184:187], v161 offset:36864
	ds_read_b128 v[188:191], v161 offset:37888
	ds_read_b128 v[192:195], v161 offset:38912
	ds_read_b128 v[196:199], v161 offset:39936
	s_cmp_lg_u32 s99, 0
	s_cbranch_scc1 .Lhsd0_2
	global_load_lds_dwordx4 v[230:231], off
.Lhsd0_2:
	v_lshl_add_u64 v[230:231], s[14:15], 0, v[146:147]
	s_mov_b32 m0, s28
	s_nop 0
	s_cmp_lg_u32 s99, 0
	s_cbranch_scc1 .Lhsd0_3
	global_load_lds_dwordx4 v[230:231], off
.Lhsd0_3:
	s_waitcnt lgkmcnt(8)
	s_barrier
	s_waitcnt lgkmcnt(0)
	s_setprio 1
	s_waitcnt lgkmcnt(0)
	v_mfma_f32_16x16x32_bf16 v[142:145], v[98:101], v[152:155], v[142:145]
	v_mfma_f32_16x16x32_bf16 v[138:141], v[106:109], v[152:155], v[138:141]
	v_mfma_f32_16x16x32_bf16 v[134:137], v[98:101], v[176:179], v[134:137]
	v_mfma_f32_16x16x32_bf16 v[122:125], v[106:109], v[176:179], v[122:125]
	v_mfma_f32_16x16x32_bf16 v[94:97], v[98:101], v[184:187], v[94:97]
	v_mfma_f32_16x16x32_bf16 v[90:93], v[106:109], v[184:187], v[90:93]
	v_mfma_f32_16x16x32_bf16 v[86:89], v[98:101], v[192:195], v[86:89]
	v_mfma_f32_16x16x32_bf16 v[74:77], v[106:109], v[192:195], v[74:77]
	v_mfma_f32_16x16x32_bf16 v[142:145], v[102:105], v[156:159], v[142:145]
	v_mfma_f32_16x16x32_bf16 v[138:141], v[110:113], v[156:159], v[138:141]
	v_mfma_f32_16x16x32_bf16 v[134:137], v[102:105], v[180:183], v[134:137]
	v_mfma_f32_16x16x32_bf16 v[122:125], v[110:113], v[180:183], v[122:125]
	v_mfma_f32_16x16x32_bf16 v[94:97], v[102:105], v[188:191], v[94:97]
	v_mfma_f32_16x16x32_bf16 v[90:93], v[110:113], v[188:191], v[90:93]
	v_mfma_f32_16x16x32_bf16 v[86:89], v[102:105], v[196:199], v[86:89]
	v_mfma_f32_16x16x32_bf16 v[74:77], v[110:113], v[196:199], v[74:77]
	s_setprio 0
	s_barrier
	s_add_i32 s20, 0, 0x1c000
	s_add_i32 s14, s44, s23
	v_add_u32_e32 v169, s20, v160
	v_lshl_add_u64 v[172:173], v[172:173], 0, s[92:93]
	s_mov_b32 m0, s14
	ds_read_b128 v[230:233], v169
	ds_read_b128 v[234:237], v169 offset:1024
	ds_read_b128 v[238:241], v169 offset:2048
	ds_read_b128 v[242:245], v169 offset:3072
	global_load_lds_dwordx4 v[172:173], off
	v_lshl_add_u64 v[172:173], v[174:175], 0, s[92:93]
	s_add_i32 m0, s14, 0x2000
	s_nop 0
	global_load_lds_dwordx4 v[172:173], off
	s_barrier
	s_waitcnt lgkmcnt(0)
	s_setprio 1
	s_waitcnt lgkmcnt(0)
	v_mfma_f32_16x16x32_bf16 v[130:133], v[230:233], v[152:155], v[130:133]
	v_mfma_f32_16x16x32_bf16 v[126:129], v[238:241], v[152:155], v[126:129]
	v_mfma_f32_16x16x32_bf16 v[118:121], v[230:233], v[176:179], v[118:121]
	v_mfma_f32_16x16x32_bf16 v[114:117], v[238:241], v[176:179], v[114:117]
	v_mfma_f32_16x16x32_bf16 v[82:85], v[230:233], v[184:187], v[82:85]
	v_mfma_f32_16x16x32_bf16 v[78:81], v[238:241], v[184:187], v[78:81]
	v_mfma_f32_16x16x32_bf16 v[70:73], v[230:233], v[192:195], v[70:73]
	v_mfma_f32_16x16x32_bf16 v[66:69], v[238:241], v[192:195], v[66:69]
	v_mfma_f32_16x16x32_bf16 v[130:133], v[234:237], v[156:159], v[130:133]
	v_mfma_f32_16x16x32_bf16 v[126:129], v[242:245], v[156:159], v[126:129]
	v_mfma_f32_16x16x32_bf16 v[118:121], v[234:237], v[180:183], v[118:121]
	v_mfma_f32_16x16x32_bf16 v[114:117], v[242:245], v[180:183], v[114:117]
	v_mfma_f32_16x16x32_bf16 v[82:85], v[234:237], v[188:191], v[82:85]
	v_mfma_f32_16x16x32_bf16 v[78:81], v[242:245], v[188:191], v[78:81]
	v_mfma_f32_16x16x32_bf16 v[70:73], v[234:237], v[196:199], v[70:73]
	v_mfma_f32_16x16x32_bf16 v[66:69], v[242:245], v[196:199], v[66:69]
	s_setprio 0
	s_mov_b32 m0, s31
	v_lshl_add_u64 v[172:173], v[200:201], 0, s[92:93]
	s_barrier
	ds_read_b128 v[152:155], v161 offset:49152
	ds_read_b128 v[156:159], v161 offset:50176
	ds_read_b128 v[176:179], v161 offset:51200
	ds_read_b128 v[180:183], v161 offset:52224
	ds_read_b128 v[184:187], v161 offset:53248
	ds_read_b128 v[188:191], v161 offset:54272
	ds_read_b128 v[192:195], v161 offset:55296
	ds_read_b128 v[196:199], v161 offset:56320
	global_load_lds_dwordx4 v[172:173], off
	v_lshl_add_u64 v[172:173], v[210:211], 0, s[92:93]
	s_mov_b32 m0, s34
	s_nop 0
	global_load_lds_dwordx4 v[172:173], off
	s_barrier
	s_waitcnt lgkmcnt(0)
	s_setprio 1
	s_waitcnt lgkmcnt(0)
	s_cmp_lg_u32 s99, 0
	s_cbranch_scc1 .Lfd_skip7
	v_mfma_f32_16x16x32_bf16 v[62:65], v[98:101], v[152:155], v[62:65]
	v_mfma_f32_16x16x32_bf16 v[58:61], v[106:109], v[152:155], v[58:61]
	v_mfma_f32_16x16x32_bf16 v[54:57], v[98:101], v[176:179], v[54:57]
	v_mfma_f32_16x16x32_bf16 v[42:45], v[106:109], v[176:179], v[42:45]
	v_mfma_f32_16x16x32_bf16 v[30:33], v[98:101], v[184:187], v[30:33]
	v_mfma_f32_16x16x32_bf16 v[26:29], v[106:109], v[184:187], v[26:29]
	v_mfma_f32_16x16x32_bf16 v[22:25], v[98:101], v[192:195], v[22:25]
	v_mfma_f32_16x16x32_bf16 v[18:21], v[106:109], v[192:195], v[18:21]
	v_mfma_f32_16x16x32_bf16 v[62:65], v[102:105], v[156:159], v[62:65]
	v_mfma_f32_16x16x32_bf16 v[58:61], v[110:113], v[156:159], v[58:61]
	v_mfma_f32_16x16x32_bf16 v[54:57], v[102:105], v[180:183], v[54:57]
	v_mfma_f32_16x16x32_bf16 v[42:45], v[110:113], v[180:183], v[42:45]
	v_mfma_f32_16x16x32_bf16 v[30:33], v[102:105], v[188:191], v[30:33]
	v_mfma_f32_16x16x32_bf16 v[26:29], v[110:113], v[188:191], v[26:29]
	v_mfma_f32_16x16x32_bf16 v[22:25], v[102:105], v[196:199], v[22:25]
	v_mfma_f32_16x16x32_bf16 v[18:21], v[110:113], v[196:199], v[18:21]
